# v_b half of the k_b|v_b tile: in-register quad transpose, 32 dwordx2 stores per wave instead of 128 two-byte stores
# baseline (speedup 1.0000x reference)
; __device__ __forceinline__ unsigned cvt_pk_bf16(float lo, float hi) { const f32x2_t v = {lo, hi}; const bf16x2_t r = __builtin_convertvector(v, bf16x2_t); return __builtin_bit_cast(unsigned, r); }
;     __device__ __forceinline__ void operator()(AccT& acc, const Unit& u, int wr, int wc, int fr, int fq) const {
;     ...
;         else if (pn == 6) {
;             if (wc < 2) qk(acc, row0, wr, fr, fq, KB, 128, 64 * wc, kn_b, 1.0f, true);
;             else {
; #pragma unroll
;                 for (int ai = 0; ai < 2; ++ai)
; #pragma unroll
;                     for (int m = 0; m < 4; ++m) {
;                         const int r = row0 + 128 * ai + 64 * wr + 16 * m + fr;
;                         bf16_t* base = VBT + ((size_t)(r >> 3) * 128 + 64 * (wc - 2) + 8 * fq) * 8 + (r & 7);
; #pragma unroll
;                         for (int bj = 0; bj < 2; ++bj)
; #pragma unroll
;                             for (int n = 0; n < 2; ++n) { const f32x4 x = acc[ai][bj][m][n];
;                                 const unsigned p0 = cvt_pk_bf16(x[0], x[1]), p1 = cvt_pk_bf16(x[2], x[3]);
;                                 bf16_t* q = base + (32 * bj + 4 * n) * 8;
;                                 q[0] = (bf16_t)(p0 & 0xffffu); q[8] = (bf16_t)(p0 >> 16); q[16] = (bf16_t)(p1 & 0xffffu); q[24] = (bf16_t)(p1 >> 16); }
;                     }
.LBB0_196:
	s_andn2_b64 vcc, exec, s[40:41]
	s_cbranch_vccnz .LBB0_201
	s_andn2_b64 vcc, exec, s[80:81]
	s_mov_b64 s[40:41], -1
	s_cbranch_vccnz .LBB0_199
	s_mov_b32 vcc_lo, 0x55555555
	s_mov_b32 vcc_hi, 0x55555555
	v_mov_b32_e32 v144, 0x03020706
	v_mov_b32_e32 v145, 0x05040100
	v_and_b32_e32 v146, 15, v190
	v_cndmask_b32_e32 v148, v144, v145, vcc
	v_and_b32_e32 v144, 3, v146
	v_lshlrev_b32_e32 v144, 4, v144
	v_bfe_u32 v145, v146, 2, 1
	v_lshl_add_u32 v144, v145, 3, v144
	v_and_b32_e32 v145, 7, v146
	v_lshlrev_b32_e32 v145, 1, v145
	v_sub_u32_e32 v144, v144, v145
	v_mov_b32_e32 v145, 0
	v_lshl_add_u64 v[142:143], v[168:169], 0, v[144:145]
	s_mov_b32 vcc_lo, 0x33333333
	s_mov_b32 vcc_hi, 0x33333333
	v_add_u32_e32 v149, s31, v153
	v_ashrrev_i32_e32 v144, 3, v149
	v_ashrrev_i32_e32 v145, 31, v144
	v_lshlrev_b64 v[146:147], 11, v[144:145]
	v_lshl_add_u64 v[140:141], v[142:143], 0, v[146:147]
	v_cvt_pk_bf16_f32 v128, v124, v125
	v_cvt_pk_bf16_f32 v129, v126, v127
	v_cvt_pk_bf16_f32 v130, v120, v121
	v_cvt_pk_bf16_f32 v131, v122, v123
	v_mov_b32_dpp v132, v128 quad_perm:[1,0,3,2] row_mask:0xf bank_mask:0xf
	v_mov_b32_dpp v133, v129 quad_perm:[1,0,3,2] row_mask:0xf bank_mask:0xf
	v_mov_b32_dpp v134, v130 quad_perm:[1,0,3,2] row_mask:0xf bank_mask:0xf
	v_mov_b32_dpp v135, v131 quad_perm:[1,0,3,2] row_mask:0xf bank_mask:0xf
	v_perm_b32 v128, v132, v128, v148
	v_perm_b32 v129, v133, v129, v148
	v_perm_b32 v130, v134, v130, v148
	v_perm_b32 v131, v135, v131, v148
	v_mov_b32_dpp v132, v128 quad_perm:[2,3,0,1] row_mask:0xf bank_mask:0xf
	v_mov_b32_dpp v133, v130 quad_perm:[2,3,0,1] row_mask:0xf bank_mask:0xf
	v_cndmask_b32_dpp v136, v129, v128, vcc quad_perm:[2,3,0,1] row_mask:0xf bank_mask:0xf
	v_cndmask_b32_dpp v138, v131, v130, vcc quad_perm:[2,3,0,1] row_mask:0xf bank_mask:0xf
	v_cndmask_b32_e32 v137, v129, v132, vcc
	v_cndmask_b32_e32 v139, v131, v133, vcc
	global_store_dwordx2 v[140:141], v[136:137], off
	global_store_dwordx2 v[140:141], v[138:139], off offset:64
	v_cvt_pk_bf16_f32 v128, v116, v117
	v_cvt_pk_bf16_f32 v129, v118, v119
	v_cvt_pk_bf16_f32 v130, v112, v113
	v_cvt_pk_bf16_f32 v131, v114, v115
	v_mov_b32_dpp v132, v128 quad_perm:[1,0,3,2] row_mask:0xf bank_mask:0xf
	v_mov_b32_dpp v133, v129 quad_perm:[1,0,3,2] row_mask:0xf bank_mask:0xf
	v_mov_b32_dpp v134, v130 quad_perm:[1,0,3,2] row_mask:0xf bank_mask:0xf
	v_mov_b32_dpp v135, v131 quad_perm:[1,0,3,2] row_mask:0xf bank_mask:0xf
	v_perm_b32 v128, v132, v128, v148
	v_perm_b32 v129, v133, v129, v148
	v_perm_b32 v130, v134, v130, v148
	v_perm_b32 v131, v135, v131, v148
	v_mov_b32_dpp v132, v128 quad_perm:[2,3,0,1] row_mask:0xf bank_mask:0xf
	v_mov_b32_dpp v133, v130 quad_perm:[2,3,0,1] row_mask:0xf bank_mask:0xf
	v_cndmask_b32_dpp v136, v129, v128, vcc quad_perm:[2,3,0,1] row_mask:0xf bank_mask:0xf
	v_cndmask_b32_dpp v138, v131, v130, vcc quad_perm:[2,3,0,1] row_mask:0xf bank_mask:0xf
	v_cndmask_b32_e32 v137, v129, v132, vcc
	v_cndmask_b32_e32 v139, v131, v133, vcc
	global_store_dwordx2 v[140:141], v[136:137], off offset:512
	global_store_dwordx2 v[140:141], v[138:139], off offset:576
	v_ashrrev_i32_e32 v144, 3, v149
	v_or_b32_e32 v144, 2, v144
	v_ashrrev_i32_e32 v145, 31, v144
	v_lshlrev_b64 v[146:147], 11, v[144:145]
	v_lshl_add_u64 v[140:141], v[142:143], 0, v[146:147]
	v_cvt_pk_bf16_f32 v128, v108, v109
	v_cvt_pk_bf16_f32 v129, v110, v111
	v_cvt_pk_bf16_f32 v130, v104, v105
	v_cvt_pk_bf16_f32 v131, v106, v107
	v_mov_b32_dpp v132, v128 quad_perm:[1,0,3,2] row_mask:0xf bank_mask:0xf
	v_mov_b32_dpp v133, v129 quad_perm:[1,0,3,2] row_mask:0xf bank_mask:0xf
	v_mov_b32_dpp v134, v130 quad_perm:[1,0,3,2] row_mask:0xf bank_mask:0xf
	v_mov_b32_dpp v135, v131 quad_perm:[1,0,3,2] row_mask:0xf bank_mask:0xf
	v_perm_b32 v128, v132, v128, v148
	v_perm_b32 v129, v133, v129, v148
	v_perm_b32 v130, v134, v130, v148
	v_perm_b32 v131, v135, v131, v148
	v_mov_b32_dpp v132, v128 quad_perm:[2,3,0,1] row_mask:0xf bank_mask:0xf
	v_mov_b32_dpp v133, v130 quad_perm:[2,3,0,1] row_mask:0xf bank_mask:0xf
	v_cndmask_b32_dpp v136, v129, v128, vcc quad_perm:[2,3,0,1] row_mask:0xf bank_mask:0xf
	v_cndmask_b32_dpp v138, v131, v130, vcc quad_perm:[2,3,0,1] row_mask:0xf bank_mask:0xf
	v_cndmask_b32_e32 v137, v129, v132, vcc
	v_cndmask_b32_e32 v139, v131, v133, vcc
	global_store_dwordx2 v[140:141], v[136:137], off
	global_store_dwordx2 v[140:141], v[138:139], off offset:64
	v_cvt_pk_bf16_f32 v128, v100, v101
	v_cvt_pk_bf16_f32 v129, v102, v103
	v_cvt_pk_bf16_f32 v130, v96, v97
	v_cvt_pk_bf16_f32 v131, v98, v99
	v_mov_b32_dpp v132, v128 quad_perm:[1,0,3,2] row_mask:0xf bank_mask:0xf
	v_mov_b32_dpp v133, v129 quad_perm:[1,0,3,2] row_mask:0xf bank_mask:0xf
	v_mov_b32_dpp v134, v130 quad_perm:[1,0,3,2] row_mask:0xf bank_mask:0xf
	v_mov_b32_dpp v135, v131 quad_perm:[1,0,3,2] row_mask:0xf bank_mask:0xf
	v_perm_b32 v128, v132, v128, v148
	v_perm_b32 v129, v133, v129, v148
	v_perm_b32 v130, v134, v130, v148
	v_perm_b32 v131, v135, v131, v148
	v_mov_b32_dpp v132, v128 quad_perm:[2,3,0,1] row_mask:0xf bank_mask:0xf
	v_mov_b32_dpp v133, v130 quad_perm:[2,3,0,1] row_mask:0xf bank_mask:0xf
	v_cndmask_b32_dpp v136, v129, v128, vcc quad_perm:[2,3,0,1] row_mask:0xf bank_mask:0xf
	v_cndmask_b32_dpp v138, v131, v130, vcc quad_perm:[2,3,0,1] row_mask:0xf bank_mask:0xf
	v_cndmask_b32_e32 v137, v129, v132, vcc
	v_cndmask_b32_e32 v139, v131, v133, vcc
	global_store_dwordx2 v[140:141], v[136:137], off offset:512
	global_store_dwordx2 v[140:141], v[138:139], off offset:576
	v_ashrrev_i32_e32 v144, 3, v149
	v_or_b32_e32 v144, 4, v144
	v_ashrrev_i32_e32 v145, 31, v144
	v_lshlrev_b64 v[146:147], 11, v[144:145]
	v_lshl_add_u64 v[140:141], v[142:143], 0, v[146:147]
; __device__ __forceinline__ unsigned cvt_pk_bf16(float lo, float hi) { const f32x2_t v = {lo, hi}; const bf16x2_t r = __builtin_convertvector(v, bf16x2_t); return __builtin_bit_cast(unsigned, r); }
;     __device__ __forceinline__ void operator()(AccT& acc, const Unit& u, int wr, int wc, int fr, int fq) const {
;     ...
;                     for (int m = 0; m < 4; ++m) {
;                         const int r = row0 + 128 * ai + 64 * wr + 16 * m + fr;
;                         bf16_t* base = VBT + ((size_t)(r >> 3) * 128 + 64 * (wc - 2) + 8 * fq) * 8 + (r & 7);
; #pragma unroll
;                         for (int bj = 0; bj < 2; ++bj)
; #pragma unroll
;                             for (int n = 0; n < 2; ++n) { const f32x4 x = acc[ai][bj][m][n];
;                                 const unsigned p0 = cvt_pk_bf16(x[0], x[1]), p1 = cvt_pk_bf16(x[2], x[3]);
;                                 bf16_t* q = base + (32 * bj + 4 * n) * 8;
;                                 q[0] = (bf16_t)(p0 & 0xffffu); q[8] = (bf16_t)(p0 >> 16); q[16] = (bf16_t)(p1 & 0xffffu); q[24] = (bf16_t)(p1 >> 16); }
;                     }
	v_cvt_pk_bf16_f32 v128, v92, v93
	v_cvt_pk_bf16_f32 v129, v94, v95
	v_cvt_pk_bf16_f32 v130, v88, v89
	v_cvt_pk_bf16_f32 v131, v90, v91
	v_mov_b32_dpp v132, v128 quad_perm:[1,0,3,2] row_mask:0xf bank_mask:0xf
	v_mov_b32_dpp v133, v129 quad_perm:[1,0,3,2] row_mask:0xf bank_mask:0xf
	v_mov_b32_dpp v134, v130 quad_perm:[1,0,3,2] row_mask:0xf bank_mask:0xf
	v_mov_b32_dpp v135, v131 quad_perm:[1,0,3,2] row_mask:0xf bank_mask:0xf
	v_perm_b32 v128, v132, v128, v148
	v_perm_b32 v129, v133, v129, v148
	v_perm_b32 v130, v134, v130, v148
	v_perm_b32 v131, v135, v131, v148
	v_mov_b32_dpp v132, v128 quad_perm:[2,3,0,1] row_mask:0xf bank_mask:0xf
	v_mov_b32_dpp v133, v130 quad_perm:[2,3,0,1] row_mask:0xf bank_mask:0xf
	v_cndmask_b32_dpp v136, v129, v128, vcc quad_perm:[2,3,0,1] row_mask:0xf bank_mask:0xf
	v_cndmask_b32_dpp v138, v131, v130, vcc quad_perm:[2,3,0,1] row_mask:0xf bank_mask:0xf
	v_cndmask_b32_e32 v137, v129, v132, vcc
	v_cndmask_b32_e32 v139, v131, v133, vcc
	global_store_dwordx2 v[140:141], v[136:137], off
	global_store_dwordx2 v[140:141], v[138:139], off offset:64
	v_cvt_pk_bf16_f32 v128, v84, v85
	v_cvt_pk_bf16_f32 v129, v86, v87
	v_cvt_pk_bf16_f32 v130, v80, v81
	v_cvt_pk_bf16_f32 v131, v82, v83
	v_mov_b32_dpp v132, v128 quad_perm:[1,0,3,2] row_mask:0xf bank_mask:0xf
	v_mov_b32_dpp v133, v129 quad_perm:[1,0,3,2] row_mask:0xf bank_mask:0xf
	v_mov_b32_dpp v134, v130 quad_perm:[1,0,3,2] row_mask:0xf bank_mask:0xf
	v_mov_b32_dpp v135, v131 quad_perm:[1,0,3,2] row_mask:0xf bank_mask:0xf
	v_perm_b32 v128, v132, v128, v148
	v_perm_b32 v129, v133, v129, v148
	v_perm_b32 v130, v134, v130, v148
	v_perm_b32 v131, v135, v131, v148
	v_mov_b32_dpp v132, v128 quad_perm:[2,3,0,1] row_mask:0xf bank_mask:0xf
	v_mov_b32_dpp v133, v130 quad_perm:[2,3,0,1] row_mask:0xf bank_mask:0xf
	v_cndmask_b32_dpp v136, v129, v128, vcc quad_perm:[2,3,0,1] row_mask:0xf bank_mask:0xf
	v_cndmask_b32_dpp v138, v131, v130, vcc quad_perm:[2,3,0,1] row_mask:0xf bank_mask:0xf
	v_cndmask_b32_e32 v137, v129, v132, vcc
	v_cndmask_b32_e32 v139, v131, v133, vcc
	global_store_dwordx2 v[140:141], v[136:137], off offset:512
	global_store_dwordx2 v[140:141], v[138:139], off offset:576
	v_ashrrev_i32_e32 v144, 3, v149
	v_or_b32_e32 v144, 6, v144
	v_ashrrev_i32_e32 v145, 31, v144
	v_lshlrev_b64 v[146:147], 11, v[144:145]
	v_lshl_add_u64 v[140:141], v[142:143], 0, v[146:147]
	v_cvt_pk_bf16_f32 v128, v76, v77
	v_cvt_pk_bf16_f32 v129, v78, v79
	v_cvt_pk_bf16_f32 v130, v72, v73
	v_cvt_pk_bf16_f32 v131, v74, v75
	v_mov_b32_dpp v132, v128 quad_perm:[1,0,3,2] row_mask:0xf bank_mask:0xf
	v_mov_b32_dpp v133, v129 quad_perm:[1,0,3,2] row_mask:0xf bank_mask:0xf
	v_mov_b32_dpp v134, v130 quad_perm:[1,0,3,2] row_mask:0xf bank_mask:0xf
	v_mov_b32_dpp v135, v131 quad_perm:[1,0,3,2] row_mask:0xf bank_mask:0xf
	v_perm_b32 v128, v132, v128, v148
	v_perm_b32 v129, v133, v129, v148
	v_perm_b32 v130, v134, v130, v148
	v_perm_b32 v131, v135, v131, v148
	v_mov_b32_dpp v132, v128 quad_perm:[2,3,0,1] row_mask:0xf bank_mask:0xf
	v_mov_b32_dpp v133, v130 quad_perm:[2,3,0,1] row_mask:0xf bank_mask:0xf
	v_cndmask_b32_dpp v136, v129, v128, vcc quad_perm:[2,3,0,1] row_mask:0xf bank_mask:0xf
	v_cndmask_b32_dpp v138, v131, v130, vcc quad_perm:[2,3,0,1] row_mask:0xf bank_mask:0xf
	v_cndmask_b32_e32 v137, v129, v132, vcc
	v_cndmask_b32_e32 v139, v131, v133, vcc
	global_store_dwordx2 v[140:141], v[136:137], off
	global_store_dwordx2 v[140:141], v[138:139], off offset:64
	v_cvt_pk_bf16_f32 v128, v68, v69
	v_cvt_pk_bf16_f32 v129, v70, v71
	v_cvt_pk_bf16_f32 v130, v64, v65
	v_cvt_pk_bf16_f32 v131, v66, v67
	v_mov_b32_dpp v132, v128 quad_perm:[1,0,3,2] row_mask:0xf bank_mask:0xf
	v_mov_b32_dpp v133, v129 quad_perm:[1,0,3,2] row_mask:0xf bank_mask:0xf
	v_mov_b32_dpp v134, v130 quad_perm:[1,0,3,2] row_mask:0xf bank_mask:0xf
	v_mov_b32_dpp v135, v131 quad_perm:[1,0,3,2] row_mask:0xf bank_mask:0xf
	v_perm_b32 v128, v132, v128, v148
	v_perm_b32 v129, v133, v129, v148
	v_perm_b32 v130, v134, v130, v148
	v_perm_b32 v131, v135, v131, v148
	v_mov_b32_dpp v132, v128 quad_perm:[2,3,0,1] row_mask:0xf bank_mask:0xf
	v_mov_b32_dpp v133, v130 quad_perm:[2,3,0,1] row_mask:0xf bank_mask:0xf
	v_cndmask_b32_dpp v136, v129, v128, vcc quad_perm:[2,3,0,1] row_mask:0xf bank_mask:0xf
	v_cndmask_b32_dpp v138, v131, v130, vcc quad_perm:[2,3,0,1] row_mask:0xf bank_mask:0xf
	v_cndmask_b32_e32 v137, v129, v132, vcc
	v_cndmask_b32_e32 v139, v131, v133, vcc
	global_store_dwordx2 v[140:141], v[136:137], off offset:512
	global_store_dwordx2 v[140:141], v[138:139], off offset:576
	v_add_u32_e32 v144, 0x80, v149
	v_ashrrev_i32_e32 v144, 3, v144
	v_ashrrev_i32_e32 v145, 31, v144
	v_lshlrev_b64 v[146:147], 11, v[144:145]
	v_lshl_add_u64 v[140:141], v[142:143], 0, v[146:147]
	v_cvt_pk_bf16_f32 v128, v60, v61
	v_cvt_pk_bf16_f32 v129, v62, v63
	v_cvt_pk_bf16_f32 v130, v56, v57
	v_cvt_pk_bf16_f32 v131, v58, v59
	v_mov_b32_dpp v132, v128 quad_perm:[1,0,3,2] row_mask:0xf bank_mask:0xf
	v_mov_b32_dpp v133, v129 quad_perm:[1,0,3,2] row_mask:0xf bank_mask:0xf
	v_mov_b32_dpp v134, v130 quad_perm:[1,0,3,2] row_mask:0xf bank_mask:0xf
	v_mov_b32_dpp v135, v131 quad_perm:[1,0,3,2] row_mask:0xf bank_mask:0xf
	v_perm_b32 v128, v132, v128, v148
	v_perm_b32 v129, v133, v129, v148
	v_perm_b32 v130, v134, v130, v148
	v_perm_b32 v131, v135, v131, v148
	v_mov_b32_dpp v132, v128 quad_perm:[2,3,0,1] row_mask:0xf bank_mask:0xf
	v_mov_b32_dpp v133, v130 quad_perm:[2,3,0,1] row_mask:0xf bank_mask:0xf
	v_cndmask_b32_dpp v136, v129, v128, vcc quad_perm:[2,3,0,1] row_mask:0xf bank_mask:0xf
	v_cndmask_b32_dpp v138, v131, v130, vcc quad_perm:[2,3,0,1] row_mask:0xf bank_mask:0xf
; __device__ __forceinline__ unsigned cvt_pk_bf16(float lo, float hi) { const f32x2_t v = {lo, hi}; const bf16x2_t r = __builtin_convertvector(v, bf16x2_t); return __builtin_bit_cast(unsigned, r); }
;     __device__ __forceinline__ void operator()(AccT& acc, const Unit& u, int wr, int wc, int fr, int fq) const {
;     ...
;                     for (int m = 0; m < 4; ++m) {
;                         const int r = row0 + 128 * ai + 64 * wr + 16 * m + fr;
;                         bf16_t* base = VBT + ((size_t)(r >> 3) * 128 + 64 * (wc - 2) + 8 * fq) * 8 + (r & 7);
; #pragma unroll
;                         for (int bj = 0; bj < 2; ++bj)
; #pragma unroll
;                             for (int n = 0; n < 2; ++n) { const f32x4 x = acc[ai][bj][m][n];
;                                 const unsigned p0 = cvt_pk_bf16(x[0], x[1]), p1 = cvt_pk_bf16(x[2], x[3]);
;                                 bf16_t* q = base + (32 * bj + 4 * n) * 8;
;                                 q[0] = (bf16_t)(p0 & 0xffffu); q[8] = (bf16_t)(p0 >> 16); q[16] = (bf16_t)(p1 & 0xffffu); q[24] = (bf16_t)(p1 >> 16); }
;                     }
	v_cndmask_b32_e32 v137, v129, v132, vcc
	v_cndmask_b32_e32 v139, v131, v133, vcc
	global_store_dwordx2 v[140:141], v[136:137], off
	global_store_dwordx2 v[140:141], v[138:139], off offset:64
	v_cvt_pk_bf16_f32 v128, v52, v53
	v_cvt_pk_bf16_f32 v129, v54, v55
	v_cvt_pk_bf16_f32 v130, v48, v49
	v_cvt_pk_bf16_f32 v131, v50, v51
	v_mov_b32_dpp v132, v128 quad_perm:[1,0,3,2] row_mask:0xf bank_mask:0xf
	v_mov_b32_dpp v133, v129 quad_perm:[1,0,3,2] row_mask:0xf bank_mask:0xf
	v_mov_b32_dpp v134, v130 quad_perm:[1,0,3,2] row_mask:0xf bank_mask:0xf
	v_mov_b32_dpp v135, v131 quad_perm:[1,0,3,2] row_mask:0xf bank_mask:0xf
	v_perm_b32 v128, v132, v128, v148
	v_perm_b32 v129, v133, v129, v148
	v_perm_b32 v130, v134, v130, v148
	v_perm_b32 v131, v135, v131, v148
	v_mov_b32_dpp v132, v128 quad_perm:[2,3,0,1] row_mask:0xf bank_mask:0xf
	v_mov_b32_dpp v133, v130 quad_perm:[2,3,0,1] row_mask:0xf bank_mask:0xf
	v_cndmask_b32_dpp v136, v129, v128, vcc quad_perm:[2,3,0,1] row_mask:0xf bank_mask:0xf
	v_cndmask_b32_dpp v138, v131, v130, vcc quad_perm:[2,3,0,1] row_mask:0xf bank_mask:0xf
	v_cndmask_b32_e32 v137, v129, v132, vcc
	v_cndmask_b32_e32 v139, v131, v133, vcc
	global_store_dwordx2 v[140:141], v[136:137], off offset:512
	global_store_dwordx2 v[140:141], v[138:139], off offset:576
	v_add_u32_e32 v144, 0x90, v149
	v_ashrrev_i32_e32 v144, 3, v144
	v_ashrrev_i32_e32 v145, 31, v144
	v_lshlrev_b64 v[146:147], 11, v[144:145]
	v_lshl_add_u64 v[140:141], v[142:143], 0, v[146:147]
	v_cvt_pk_bf16_f32 v128, v44, v45
	v_cvt_pk_bf16_f32 v129, v46, v47
	v_cvt_pk_bf16_f32 v130, v40, v41
	v_cvt_pk_bf16_f32 v131, v42, v43
	v_mov_b32_dpp v132, v128 quad_perm:[1,0,3,2] row_mask:0xf bank_mask:0xf
	v_mov_b32_dpp v133, v129 quad_perm:[1,0,3,2] row_mask:0xf bank_mask:0xf
	v_mov_b32_dpp v134, v130 quad_perm:[1,0,3,2] row_mask:0xf bank_mask:0xf
	v_mov_b32_dpp v135, v131 quad_perm:[1,0,3,2] row_mask:0xf bank_mask:0xf
	v_perm_b32 v128, v132, v128, v148
	v_perm_b32 v129, v133, v129, v148
	v_perm_b32 v130, v134, v130, v148
	v_perm_b32 v131, v135, v131, v148
	v_mov_b32_dpp v132, v128 quad_perm:[2,3,0,1] row_mask:0xf bank_mask:0xf
	v_mov_b32_dpp v133, v130 quad_perm:[2,3,0,1] row_mask:0xf bank_mask:0xf
	v_cndmask_b32_dpp v136, v129, v128, vcc quad_perm:[2,3,0,1] row_mask:0xf bank_mask:0xf
	v_cndmask_b32_dpp v138, v131, v130, vcc quad_perm:[2,3,0,1] row_mask:0xf bank_mask:0xf
	v_cndmask_b32_e32 v137, v129, v132, vcc
	v_cndmask_b32_e32 v139, v131, v133, vcc
	global_store_dwordx2 v[140:141], v[136:137], off
	global_store_dwordx2 v[140:141], v[138:139], off offset:64
	v_cvt_pk_bf16_f32 v128, v36, v37
	v_cvt_pk_bf16_f32 v129, v38, v39
	v_cvt_pk_bf16_f32 v130, v32, v33
	v_cvt_pk_bf16_f32 v131, v34, v35
	v_mov_b32_dpp v132, v128 quad_perm:[1,0,3,2] row_mask:0xf bank_mask:0xf
	v_mov_b32_dpp v133, v129 quad_perm:[1,0,3,2] row_mask:0xf bank_mask:0xf
	v_mov_b32_dpp v134, v130 quad_perm:[1,0,3,2] row_mask:0xf bank_mask:0xf
	v_mov_b32_dpp v135, v131 quad_perm:[1,0,3,2] row_mask:0xf bank_mask:0xf
	v_perm_b32 v128, v132, v128, v148
	v_perm_b32 v129, v133, v129, v148
	v_perm_b32 v130, v134, v130, v148
	v_perm_b32 v131, v135, v131, v148
	v_mov_b32_dpp v132, v128 quad_perm:[2,3,0,1] row_mask:0xf bank_mask:0xf
	v_mov_b32_dpp v133, v130 quad_perm:[2,3,0,1] row_mask:0xf bank_mask:0xf
	v_cndmask_b32_dpp v136, v129, v128, vcc quad_perm:[2,3,0,1] row_mask:0xf bank_mask:0xf
	v_cndmask_b32_dpp v138, v131, v130, vcc quad_perm:[2,3,0,1] row_mask:0xf bank_mask:0xf
	v_cndmask_b32_e32 v137, v129, v132, vcc
	v_cndmask_b32_e32 v139, v131, v133, vcc
	global_store_dwordx2 v[140:141], v[136:137], off offset:512
	global_store_dwordx2 v[140:141], v[138:139], off offset:576
	v_add_u32_e32 v144, 0xa0, v149
	v_ashrrev_i32_e32 v144, 3, v144
	v_ashrrev_i32_e32 v145, 31, v144
	v_lshlrev_b64 v[146:147], 11, v[144:145]
	v_lshl_add_u64 v[140:141], v[142:143], 0, v[146:147]
	v_cvt_pk_bf16_f32 v128, v28, v29
	v_cvt_pk_bf16_f32 v129, v30, v31
	v_cvt_pk_bf16_f32 v130, v24, v25
	v_cvt_pk_bf16_f32 v131, v26, v27
	v_mov_b32_dpp v132, v128 quad_perm:[1,0,3,2] row_mask:0xf bank_mask:0xf
	v_mov_b32_dpp v133, v129 quad_perm:[1,0,3,2] row_mask:0xf bank_mask:0xf
	v_mov_b32_dpp v134, v130 quad_perm:[1,0,3,2] row_mask:0xf bank_mask:0xf
; __device__ __forceinline__ unsigned cvt_pk_bf16(float lo, float hi) { const f32x2_t v = {lo, hi}; const bf16x2_t r = __builtin_convertvector(v, bf16x2_t); return __builtin_bit_cast(unsigned, r); }
;     __device__ __forceinline__ void operator()(AccT& acc, const Unit& u, int wr, int wc, int fr, int fq) const {
;     ...
;                     for (int m = 0; m < 4; ++m) {
;                         const int r = row0 + 128 * ai + 64 * wr + 16 * m + fr;
;                         bf16_t* base = VBT + ((size_t)(r >> 3) * 128 + 64 * (wc - 2) + 8 * fq) * 8 + (r & 7);
; #pragma unroll
;                         for (int bj = 0; bj < 2; ++bj)
; #pragma unroll
;                             for (int n = 0; n < 2; ++n) { const f32x4 x = acc[ai][bj][m][n];
;                                 const unsigned p0 = cvt_pk_bf16(x[0], x[1]), p1 = cvt_pk_bf16(x[2], x[3]);
;                                 bf16_t* q = base + (32 * bj + 4 * n) * 8;
;                                 q[0] = (bf16_t)(p0 & 0xffffu); q[8] = (bf16_t)(p0 >> 16); q[16] = (bf16_t)(p1 & 0xffffu); q[24] = (bf16_t)(p1 >> 16); }
;                     }
	v_mov_b32_dpp v135, v131 quad_perm:[1,0,3,2] row_mask:0xf bank_mask:0xf
	v_perm_b32 v128, v132, v128, v148
	v_perm_b32 v129, v133, v129, v148
	v_perm_b32 v130, v134, v130, v148
	v_perm_b32 v131, v135, v131, v148
	v_mov_b32_dpp v132, v128 quad_perm:[2,3,0,1] row_mask:0xf bank_mask:0xf
	v_mov_b32_dpp v133, v130 quad_perm:[2,3,0,1] row_mask:0xf bank_mask:0xf
	v_cndmask_b32_dpp v136, v129, v128, vcc quad_perm:[2,3,0,1] row_mask:0xf bank_mask:0xf
	v_cndmask_b32_dpp v138, v131, v130, vcc quad_perm:[2,3,0,1] row_mask:0xf bank_mask:0xf
	v_cndmask_b32_e32 v137, v129, v132, vcc
	v_cndmask_b32_e32 v139, v131, v133, vcc
	global_store_dwordx2 v[140:141], v[136:137], off
	global_store_dwordx2 v[140:141], v[138:139], off offset:64
	v_cvt_pk_bf16_f32 v128, v20, v21
	v_cvt_pk_bf16_f32 v129, v22, v23
	v_cvt_pk_bf16_f32 v130, v16, v17
	v_cvt_pk_bf16_f32 v131, v18, v19
	v_mov_b32_dpp v132, v128 quad_perm:[1,0,3,2] row_mask:0xf bank_mask:0xf
	v_mov_b32_dpp v133, v129 quad_perm:[1,0,3,2] row_mask:0xf bank_mask:0xf
	v_mov_b32_dpp v134, v130 quad_perm:[1,0,3,2] row_mask:0xf bank_mask:0xf
	v_mov_b32_dpp v135, v131 quad_perm:[1,0,3,2] row_mask:0xf bank_mask:0xf
	v_perm_b32 v128, v132, v128, v148
	v_perm_b32 v129, v133, v129, v148
	v_perm_b32 v130, v134, v130, v148
	v_perm_b32 v131, v135, v131, v148
	v_mov_b32_dpp v132, v128 quad_perm:[2,3,0,1] row_mask:0xf bank_mask:0xf
	v_mov_b32_dpp v133, v130 quad_perm:[2,3,0,1] row_mask:0xf bank_mask:0xf
	v_cndmask_b32_dpp v136, v129, v128, vcc quad_perm:[2,3,0,1] row_mask:0xf bank_mask:0xf
	v_cndmask_b32_dpp v138, v131, v130, vcc quad_perm:[2,3,0,1] row_mask:0xf bank_mask:0xf
	v_cndmask_b32_e32 v137, v129, v132, vcc
	v_cndmask_b32_e32 v139, v131, v133, vcc
	global_store_dwordx2 v[140:141], v[136:137], off offset:512
	global_store_dwordx2 v[140:141], v[138:139], off offset:576
	v_add_u32_e32 v144, 0xb0, v149
	v_ashrrev_i32_e32 v144, 3, v144
	v_ashrrev_i32_e32 v145, 31, v144
	v_lshlrev_b64 v[146:147], 11, v[144:145]
	v_lshl_add_u64 v[140:141], v[142:143], 0, v[146:147]
	v_cvt_pk_bf16_f32 v128, v12, v13
	v_cvt_pk_bf16_f32 v129, v14, v15
	v_cvt_pk_bf16_f32 v130, v8, v9
	v_cvt_pk_bf16_f32 v131, v10, v11
	v_mov_b32_dpp v132, v128 quad_perm:[1,0,3,2] row_mask:0xf bank_mask:0xf
	v_mov_b32_dpp v133, v129 quad_perm:[1,0,3,2] row_mask:0xf bank_mask:0xf
	v_mov_b32_dpp v134, v130 quad_perm:[1,0,3,2] row_mask:0xf bank_mask:0xf
	v_mov_b32_dpp v135, v131 quad_perm:[1,0,3,2] row_mask:0xf bank_mask:0xf
	v_perm_b32 v128, v132, v128, v148
	v_perm_b32 v129, v133, v129, v148
	v_perm_b32 v130, v134, v130, v148
	v_perm_b32 v131, v135, v131, v148
	v_mov_b32_dpp v132, v128 quad_perm:[2,3,0,1] row_mask:0xf bank_mask:0xf
	v_mov_b32_dpp v133, v130 quad_perm:[2,3,0,1] row_mask:0xf bank_mask:0xf
	v_cndmask_b32_dpp v136, v129, v128, vcc quad_perm:[2,3,0,1] row_mask:0xf bank_mask:0xf
	v_cndmask_b32_dpp v138, v131, v130, vcc quad_perm:[2,3,0,1] row_mask:0xf bank_mask:0xf
	v_cndmask_b32_e32 v137, v129, v132, vcc
	v_cndmask_b32_e32 v139, v131, v133, vcc
	global_store_dwordx2 v[140:141], v[136:137], off
	global_store_dwordx2 v[140:141], v[138:139], off offset:64
	v_cvt_pk_bf16_f32 v128, v4, v5
	v_cvt_pk_bf16_f32 v129, v6, v7
	v_cvt_pk_bf16_f32 v130, v0, v1
	v_cvt_pk_bf16_f32 v131, v2, v3
	v_mov_b32_dpp v132, v128 quad_perm:[1,0,3,2] row_mask:0xf bank_mask:0xf
	v_mov_b32_dpp v133, v129 quad_perm:[1,0,3,2] row_mask:0xf bank_mask:0xf
	v_mov_b32_dpp v134, v130 quad_perm:[1,0,3,2] row_mask:0xf bank_mask:0xf
	v_mov_b32_dpp v135, v131 quad_perm:[1,0,3,2] row_mask:0xf bank_mask:0xf
	v_perm_b32 v128, v132, v128, v148
	v_perm_b32 v129, v133, v129, v148
	v_perm_b32 v130, v134, v130, v148
	v_perm_b32 v131, v135, v131, v148
	v_mov_b32_dpp v132, v128 quad_perm:[2,3,0,1] row_mask:0xf bank_mask:0xf
	v_mov_b32_dpp v133, v130 quad_perm:[2,3,0,1] row_mask:0xf bank_mask:0xf
	v_cndmask_b32_dpp v136, v129, v128, vcc quad_perm:[2,3,0,1] row_mask:0xf bank_mask:0xf
	v_cndmask_b32_dpp v138, v131, v130, vcc quad_perm:[2,3,0,1] row_mask:0xf bank_mask:0xf
	v_cndmask_b32_e32 v137, v129, v132, vcc
	v_cndmask_b32_e32 v139, v131, v133, vcc
	global_store_dwordx2 v[140:141], v[136:137], off offset:512
	global_store_dwordx2 v[140:141], v[138:139], off offset:576
	s_mov_b64 s[40:41], 0
